# scan item setup: the 32 serialised C-fragment load pairs are issued back to back into own registers with a single wait
# baseline (speedup 1.0000x reference)
.LBB0_548:
	s_or_b64 exec, exec, s[46:47]
	v_or_b32_e32 v48, v62, v134
	v_mov_b32_e32 v49, v63
	v_lshlrev_b64 v[48:49], 2, v[48:49]
	v_lshl_add_u64 v[52:53], v[136:137], 0, v[48:49]
	v_lshl_add_u64 v[66:67], v[138:139], 0, v[48:49]
	global_load_dwordx4 v[48:51], v[52:53], off offset:16
	global_load_dwordx4 v[56:59], v[52:53], off
	s_nop 0
	global_load_dwordx4 v[52:55], v[66:67], off offset:16
	global_load_dwordx4 v[94:97], v[66:67], off
	v_lshl_add_u64 v[62:63], v[62:63], 0, v[122:123]
	v_mov_b32_e32 v69, 0
	v_mov_b32_e32 v73, 0
	v_mov_b32_e32 v77, 0
	s_and_saveexec_b64 s[46:47], s[44:45]
	s_cbranch_execz .LBB0_550
	v_or_b32_e32 v66, v62, v120
	v_mov_b32_e32 v67, v63
	v_lshlrev_b64 v[66:67], 2, v[66:67]
	v_lshl_add_u64 v[70:71], s[92:93], 0, v[66:67]
	v_lshl_add_u64 v[66:67], s[78:79], 0, v[66:67]
	global_load_dword v202, v[70:71], off
	global_load_dword v73, v[66:67], off
	s_nop 0
	s_nop 0
.LBB0_550:
	s_or_b64 exec, exec, s[46:47]
	v_lshl_add_u64 v[62:63], v[62:63], 0, v[120:121]
	v_lshlrev_b64 v[62:63], 2, v[62:63]
	v_mov_b32_e32 v81, 0
	s_and_saveexec_b64 s[46:47], s[44:45]
	s_cbranch_execz .LBB0_552
	v_lshl_add_u64 v[66:67], s[92:93], 0, v[62:63]
	v_lshl_add_u64 v[68:69], s[78:79], 0, v[62:63]
	global_load_dword v203, v[66:67], off offset:4
	s_nop 0
	global_load_dword v69, v[68:69], off offset:4
	s_nop 0
	s_nop 0
.LBB0_552:
	s_or_b64 exec, exec, s[46:47]
	v_mov_b32_e32 v85, 0
	v_mov_b32_e32 v89, 0
	v_mov_b32_e32 v90, 0
	s_and_saveexec_b64 s[46:47], s[44:45]
	s_cbranch_execz .LBB0_554
	v_lshl_add_u64 v[66:67], s[92:93], 0, v[62:63]
	v_lshl_add_u64 v[70:71], s[78:79], 0, v[62:63]
	global_load_dword v204, v[66:67], off offset:8
	global_load_dword v89, v[70:71], off offset:8
	s_nop 0
	s_nop 0
.LBB0_554:
	s_or_b64 exec, exec, s[46:47]
	v_mov_b32_e32 v93, 0
	s_and_saveexec_b64 s[46:47], s[44:45]
	s_cbranch_execz .LBB0_556
	v_lshl_add_u64 v[66:67], s[92:93], 0, v[62:63]
	v_lshl_add_u64 v[70:71], s[78:79], 0, v[62:63]
	global_load_dword v205, v[66:67], off offset:12
	global_load_dword v85, v[70:71], off offset:12
	s_nop 0
	s_nop 0
.LBB0_556:
	s_or_b64 exec, exec, s[46:47]
	v_mov_b32_e32 v87, 0
	v_mov_b32_e32 v86, 0
	v_mov_b32_e32 v91, 0
	s_and_saveexec_b64 s[46:47], s[44:45]
	s_cbranch_execz .LBB0_558
	v_lshl_add_u64 v[66:67], s[92:93], 0, v[62:63]
	v_lshl_add_u64 v[70:71], s[78:79], 0, v[62:63]
	global_load_dword v206, v[66:67], off offset:32
	global_load_dword v86, v[70:71], off offset:32
	s_nop 0
	s_nop 0
.LBB0_558:
	s_or_b64 exec, exec, s[46:47]
	v_mov_b32_e32 v92, 0
	s_and_saveexec_b64 s[46:47], s[44:45]
	s_cbranch_execz .LBB0_560
	v_lshl_add_u64 v[66:67], s[92:93], 0, v[62:63]
	v_lshl_add_u64 v[70:71], s[78:79], 0, v[62:63]
	global_load_dword v207, v[66:67], off offset:36
	global_load_dword v87, v[70:71], off offset:36
	s_nop 0
	s_nop 0
.LBB0_560:
	s_or_b64 exec, exec, s[46:47]
	v_mov_b32_e32 v131, 0
	v_mov_b32_e32 v88, 0
	v_mov_b32_e32 v149, 0
	s_and_saveexec_b64 s[46:47], s[44:45]
	s_cbranch_execz .LBB0_562
	v_lshl_add_u64 v[66:67], s[92:93], 0, v[62:63]
	v_lshl_add_u64 v[70:71], s[78:79], 0, v[62:63]
	global_load_dword v208, v[66:67], off offset:40
	global_load_dword v88, v[70:71], off offset:40
	s_nop 0
	s_nop 0
.LBB0_562:
	s_or_b64 exec, exec, s[46:47]
	v_mov_b32_e32 v150, 0
	s_and_saveexec_b64 s[46:47], s[44:45]
	s_cbranch_execz .LBB0_564
	v_lshl_add_u64 v[66:67], s[92:93], 0, v[62:63]
	v_lshl_add_u64 v[70:71], s[78:79], 0, v[62:63]
	global_load_dword v209, v[66:67], off offset:44
	global_load_dword v131, v[70:71], off offset:44
	s_nop 0
	s_nop 0
.LBB0_564:
	s_or_b64 exec, exec, s[46:47]
	v_mov_b32_e32 v83, 0
	v_mov_b32_e32 v82, 0
	v_mov_b32_e32 v151, 0
	s_and_saveexec_b64 s[46:47], s[44:45]
	s_cbranch_execz .LBB0_566
	v_lshl_add_u64 v[66:67], s[92:93], 0, v[62:63]
	v_lshl_add_u64 v[70:71], s[78:79], 0, v[62:63]
	global_load_dword v210, v[66:67], off offset:64
	global_load_dword v82, v[70:71], off offset:64
	s_nop 0
	s_nop 0
.LBB0_566:
	s_or_b64 exec, exec, s[46:47]
	v_mov_b32_e32 v152, 0
	s_and_saveexec_b64 s[46:47], s[44:45]
	s_cbranch_execz .LBB0_568
	v_lshl_add_u64 v[66:67], s[92:93], 0, v[62:63]
	v_lshl_add_u64 v[70:71], s[78:79], 0, v[62:63]
	global_load_dword v211, v[66:67], off offset:68
	global_load_dword v83, v[70:71], off offset:68
	s_nop 0
	s_nop 0
.LBB0_568:
	s_or_b64 exec, exec, s[46:47]
	v_mov_b32_e32 v153, 0
	v_mov_b32_e32 v84, 0
	v_mov_b32_e32 v154, 0
	s_and_saveexec_b64 s[46:47], s[44:45]
	s_cbranch_execz .LBB0_570
	v_lshl_add_u64 v[66:67], s[92:93], 0, v[62:63]
	v_lshl_add_u64 v[70:71], s[78:79], 0, v[62:63]
	global_load_dword v212, v[66:67], off offset:72
	global_load_dword v84, v[70:71], off offset:72
	s_nop 0
	s_nop 0
.LBB0_570:
	s_or_b64 exec, exec, s[46:47]
	v_mov_b32_e32 v155, 0
	s_and_saveexec_b64 s[46:47], s[44:45]
	s_cbranch_execz .LBB0_572
	v_lshl_add_u64 v[66:67], s[92:93], 0, v[62:63]
	v_lshl_add_u64 v[70:71], s[78:79], 0, v[62:63]
	global_load_dword v213, v[66:67], off offset:76
	global_load_dword v153, v[70:71], off offset:76
	s_nop 0
	s_nop 0
.LBB0_572:
	s_or_b64 exec, exec, s[46:47]
	v_mov_b32_e32 v79, 0
	v_mov_b32_e32 v78, 0
	v_mov_b32_e32 v156, 0
	s_and_saveexec_b64 s[46:47], s[44:45]
	s_cbranch_execz .LBB0_574
	v_lshl_add_u64 v[66:67], s[92:93], 0, v[62:63]
	v_lshl_add_u64 v[70:71], s[78:79], 0, v[62:63]
	global_load_dword v214, v[66:67], off offset:96
	global_load_dword v78, v[70:71], off offset:96
	s_nop 0
	s_nop 0
.LBB0_574:
	s_or_b64 exec, exec, s[46:47]
	v_mov_b32_e32 v157, 0
	s_and_saveexec_b64 s[46:47], s[44:45]
	s_cbranch_execz .LBB0_576
	v_lshl_add_u64 v[66:67], s[92:93], 0, v[62:63]
	v_lshl_add_u64 v[70:71], s[78:79], 0, v[62:63]
	global_load_dword v215, v[66:67], off offset:100
	global_load_dword v79, v[70:71], off offset:100
	s_nop 0
	s_nop 0
.LBB0_576:
	s_or_b64 exec, exec, s[46:47]
	v_mov_b32_e32 v158, 0
	v_mov_b32_e32 v80, 0
	v_mov_b32_e32 v159, 0
	s_and_saveexec_b64 s[46:47], s[44:45]
	s_cbranch_execz .LBB0_578
	v_lshl_add_u64 v[66:67], s[92:93], 0, v[62:63]
	v_lshl_add_u64 v[70:71], s[78:79], 0, v[62:63]
	global_load_dword v216, v[66:67], off offset:104
	global_load_dword v80, v[70:71], off offset:104
	s_nop 0
	s_nop 0
.LBB0_578:
	s_or_b64 exec, exec, s[46:47]
	v_mov_b32_e32 v160, 0
	s_and_saveexec_b64 s[46:47], s[44:45]
	s_cbranch_execz .LBB0_580
	v_lshl_add_u64 v[66:67], s[92:93], 0, v[62:63]
	v_lshl_add_u64 v[70:71], s[78:79], 0, v[62:63]
	global_load_dword v217, v[66:67], off offset:108
	global_load_dword v158, v[70:71], off offset:108
	s_nop 0
	s_nop 0
.LBB0_580:
	s_or_b64 exec, exec, s[46:47]
	v_mov_b32_e32 v75, 0
	v_mov_b32_e32 v74, 0
	v_mov_b32_e32 v161, 0
	s_and_saveexec_b64 s[46:47], s[44:45]
	s_cbranch_execz .LBB0_582
	v_lshl_add_u64 v[66:67], s[92:93], 0, v[62:63]
	v_lshl_add_u64 v[70:71], s[78:79], 0, v[62:63]
	global_load_dword v218, v[66:67], off offset:128
	global_load_dword v74, v[70:71], off offset:128
	s_nop 0
	s_nop 0
.LBB0_582:
	s_or_b64 exec, exec, s[46:47]
	v_mov_b32_e32 v163, 0
	s_and_saveexec_b64 s[46:47], s[44:45]
	s_cbranch_execz .LBB0_584
	v_lshl_add_u64 v[66:67], s[92:93], 0, v[62:63]
	v_lshl_add_u64 v[70:71], s[78:79], 0, v[62:63]
	global_load_dword v219, v[66:67], off offset:132
	global_load_dword v75, v[70:71], off offset:132
	s_nop 0
	s_nop 0
.LBB0_584:
	s_or_b64 exec, exec, s[46:47]
	v_mov_b32_e32 v162, 0
	v_mov_b32_e32 v76, 0
	v_mov_b32_e32 v165, 0
	s_and_saveexec_b64 s[46:47], s[44:45]
	s_cbranch_execz .LBB0_586
	v_lshl_add_u64 v[66:67], s[92:93], 0, v[62:63]
	v_lshl_add_u64 v[70:71], s[78:79], 0, v[62:63]
	global_load_dword v220, v[66:67], off offset:136
	global_load_dword v76, v[70:71], off offset:136
	s_nop 0
	s_nop 0
.LBB0_586:
	s_or_b64 exec, exec, s[46:47]
	v_mov_b32_e32 v164, 0
	s_and_saveexec_b64 s[46:47], s[44:45]
	s_cbranch_execz .LBB0_588
	v_lshl_add_u64 v[66:67], s[92:93], 0, v[62:63]
	v_lshl_add_u64 v[70:71], s[78:79], 0, v[62:63]
	global_load_dword v221, v[66:67], off offset:140
	global_load_dword v162, v[70:71], off offset:140
	s_nop 0
	s_nop 0
.LBB0_588:
	s_or_b64 exec, exec, s[46:47]
	v_mov_b32_e32 v71, 0
	v_mov_b32_e32 v70, 0
	v_mov_b32_e32 v166, 0
	s_and_saveexec_b64 s[46:47], s[44:45]
	s_cbranch_execz .LBB0_590
	v_lshl_add_u64 v[66:67], s[92:93], 0, v[62:63]
	v_lshl_add_u64 v[166:167], s[78:79], 0, v[62:63]
	global_load_dword v222, v[66:67], off offset:160
	global_load_dword v70, v[166:167], off offset:160
	s_nop 0
	s_nop 0
.LBB0_590:
	s_or_b64 exec, exec, s[46:47]
	v_mov_b32_e32 v168, 0
	s_and_saveexec_b64 s[46:47], s[44:45]
	s_cbranch_execz .LBB0_592
	v_lshl_add_u64 v[66:67], s[92:93], 0, v[62:63]
	v_lshl_add_u64 v[168:169], s[78:79], 0, v[62:63]
	global_load_dword v223, v[66:67], off offset:164
	global_load_dword v71, v[168:169], off offset:164
	s_nop 0
	s_nop 0
.LBB0_592:
	s_or_b64 exec, exec, s[46:47]
	v_mov_b32_e32 v167, 0
	v_mov_b32_e32 v72, 0
	v_mov_b32_e32 v170, 0
	s_and_saveexec_b64 s[46:47], s[44:45]
	s_cbranch_execz .LBB0_594
	v_lshl_add_u64 v[66:67], s[92:93], 0, v[62:63]
	v_lshl_add_u64 v[170:171], s[78:79], 0, v[62:63]
	global_load_dword v224, v[66:67], off offset:168
	global_load_dword v72, v[170:171], off offset:168
	s_nop 0
	s_nop 0
.LBB0_594:
	s_or_b64 exec, exec, s[46:47]
	v_mov_b32_e32 v169, 0
	s_and_saveexec_b64 s[46:47], s[44:45]
	s_cbranch_execz .LBB0_596
	v_lshl_add_u64 v[66:67], s[92:93], 0, v[62:63]
	v_lshl_add_u64 v[172:173], s[78:79], 0, v[62:63]
	global_load_dword v225, v[66:67], off offset:172
	global_load_dword v167, v[172:173], off offset:172
	s_nop 0
	s_nop 0
.LBB0_596:
	s_or_b64 exec, exec, s[46:47]
	v_mov_b32_e32 v67, 0
	v_mov_b32_e32 v66, 0
	v_mov_b32_e32 v171, 0
	s_and_saveexec_b64 s[46:47], s[44:45]
	s_cbranch_execz .LBB0_598
	v_lshl_add_u64 v[172:173], s[92:93], 0, v[62:63]
	v_lshl_add_u64 v[174:175], s[78:79], 0, v[62:63]
	global_load_dword v226, v[172:173], off offset:192
	global_load_dword v66, v[174:175], off offset:192
	s_nop 0
	s_nop 0
.LBB0_598:
	s_or_b64 exec, exec, s[46:47]
	v_mov_b32_e32 v173, 0
	s_and_saveexec_b64 s[46:47], s[44:45]
	s_cbranch_execz .LBB0_600
	v_lshl_add_u64 v[172:173], s[92:93], 0, v[62:63]
	v_lshl_add_u64 v[174:175], s[78:79], 0, v[62:63]
	global_load_dword v227, v[172:173], off offset:196
	global_load_dword v67, v[174:175], off offset:196
	s_nop 0
	s_nop 0
.LBB0_600:
	s_or_b64 exec, exec, s[46:47]
	v_mov_b32_e32 v172, 0
	v_mov_b32_e32 v68, 0
	v_mov_b32_e32 v175, 0
	s_and_saveexec_b64 s[46:47], s[44:45]
	s_cbranch_execz .LBB0_602
	v_lshl_add_u64 v[174:175], s[92:93], 0, v[62:63]
	v_lshl_add_u64 v[192:193], s[78:79], 0, v[62:63]
	global_load_dword v228, v[174:175], off offset:200
	global_load_dword v68, v[192:193], off offset:200
	s_nop 0
	s_nop 0
.LBB0_602:
	s_or_b64 exec, exec, s[46:47]
	v_mov_b32_e32 v174, 0
	s_and_saveexec_b64 s[46:47], s[44:45]
	s_cbranch_execz .LBB0_604
	v_lshl_add_u64 v[192:193], s[92:93], 0, v[62:63]
	v_lshl_add_u64 v[194:195], s[78:79], 0, v[62:63]
	global_load_dword v229, v[192:193], off offset:204
	global_load_dword v172, v[194:195], off offset:204
	s_nop 0
	s_nop 0
.LBB0_604:
	s_or_b64 exec, exec, s[46:47]
	v_mov_b32_e32 v195, 0
	v_mov_b32_e32 v194, 0
	v_mov_b32_e32 v196, 0
	s_and_saveexec_b64 s[46:47], s[44:45]
	s_cbranch_execz .LBB0_606
	v_lshl_add_u64 v[192:193], s[92:93], 0, v[62:63]
	v_lshl_add_u64 v[196:197], s[78:79], 0, v[62:63]
	global_load_dword v230, v[192:193], off offset:224
	global_load_dword v194, v[196:197], off offset:224
	s_nop 0
	s_nop 0
.LBB0_606:
	s_or_b64 exec, exec, s[46:47]
	v_mov_b32_e32 v197, 0
	s_and_saveexec_b64 s[46:47], s[44:45]
	s_cbranch_execz .LBB0_608
	v_lshl_add_u64 v[192:193], s[92:93], 0, v[62:63]
	v_lshl_add_u64 v[198:199], s[78:79], 0, v[62:63]
	global_load_dword v231, v[192:193], off offset:228
	global_load_dword v195, v[198:199], off offset:228
	s_nop 0
	s_nop 0
.LBB0_608:
	s_or_b64 exec, exec, s[46:47]
	v_mov_b32_e32 v192, 0
	v_mov_b32_e32 v64, 0
	v_mov_b32_e32 v198, 0
	s_and_saveexec_b64 s[46:47], s[44:45]
	s_cbranch_execz .LBB0_610
	v_lshl_add_u64 v[198:199], s[92:93], 0, v[62:63]
	v_lshl_add_u64 v[200:201], s[78:79], 0, v[62:63]
	global_load_dword v232, v[198:199], off offset:232
	global_load_dword v64, v[200:201], off offset:232
	s_nop 0
	s_nop 0
.LBB0_610:
	s_or_b64 exec, exec, s[46:47]
	v_mov_b32_e32 v193, 0
	s_and_saveexec_b64 s[46:47], s[44:45]
	s_cbranch_execz .LBB0_612
	v_lshl_add_u64 v[192:193], s[92:93], 0, v[62:63]
	v_lshl_add_u64 v[62:63], s[78:79], 0, v[62:63]
	global_load_dword v233, v[192:193], off offset:236
	s_nop 0
	global_load_dword v192, v[62:63], off offset:236
	s_nop 0
	s_nop 0
.LBB0_612:
	s_or_b64 exec, exec, s[46:47]
	s_waitcnt vmcnt(0)
	s_and_saveexec_b64 s[46:47], s[44:45]
	v_xor_b32_e32 v77, 0x80000000, v202
	v_xor_b32_e32 v81, 0x80000000, v203
	v_xor_b32_e32 v90, 0x80000000, v204
	v_xor_b32_e32 v93, 0x80000000, v205
	v_xor_b32_e32 v91, 0x80000000, v206
	v_xor_b32_e32 v92, 0x80000000, v207
	v_xor_b32_e32 v149, 0x80000000, v208
	v_xor_b32_e32 v150, 0x80000000, v209
	v_xor_b32_e32 v151, 0x80000000, v210
	v_xor_b32_e32 v152, 0x80000000, v211
	v_xor_b32_e32 v154, 0x80000000, v212
	v_xor_b32_e32 v155, 0x80000000, v213
	v_xor_b32_e32 v156, 0x80000000, v214
	v_xor_b32_e32 v157, 0x80000000, v215
	v_xor_b32_e32 v159, 0x80000000, v216
	v_xor_b32_e32 v160, 0x80000000, v217
	v_xor_b32_e32 v161, 0x80000000, v218
	v_xor_b32_e32 v163, 0x80000000, v219
	v_xor_b32_e32 v165, 0x80000000, v220
	v_xor_b32_e32 v164, 0x80000000, v221
	v_xor_b32_e32 v166, 0x80000000, v222
	v_xor_b32_e32 v168, 0x80000000, v223
	v_xor_b32_e32 v170, 0x80000000, v224
	v_xor_b32_e32 v169, 0x80000000, v225
	v_xor_b32_e32 v171, 0x80000000, v226
	v_xor_b32_e32 v173, 0x80000000, v227
	v_xor_b32_e32 v175, 0x80000000, v228
	v_xor_b32_e32 v174, 0x80000000, v229
	v_xor_b32_e32 v196, 0x80000000, v230
	v_xor_b32_e32 v197, 0x80000000, v231
	v_xor_b32_e32 v198, 0x80000000, v232
	v_xor_b32_e32 v193, 0x80000000, v233
	s_or_b64 exec, exec, s[46:47]
	s_ashr_i32 s50, s39, 5
	s_andn2_b64 vcc, exec, s[76:77]
	v_ashrrev_i32_e32 v141, 31, v140
	s_cbranch_vccnz .LBB0_614
	s_ashr_i32 s51, s50, 31
	s_lshl_b64 s[46:47], s[50:51], 2
	s_or_b32 s46, s46, s38
	s_or_b64 s[46:47], s[46:47], s[80:81]
	s_lshl_b64 s[46:47], s[46:47], 12
	v_lshlrev_b64 v[62:63], 6, v[140:141]
	v_lshl_add_u64 v[62:63], s[46:47], 0, v[62:63]
	v_or_b32_e32 v62, v62, v118
	v_lshlrev_b64 v[62:63], 2, v[62:63]
	v_lshl_add_u64 v[200:201], s[72:73], 0, v[62:63]
	v_lshl_add_u64 v[62:63], s[74:75], 0, v[62:63]
	global_load_dword v135, v[200:201], off
	global_load_dword v101, v[62:63], off
	s_movk_i32 s39, 0x80
	s_branch .LBB0_615
